# v025 + HGRN scan: stage-1 read-wait-MFMA ladders software-pipelined over 4 fragment buffers in dead VGPRs v204-227, stage-2 A.V loop unrolled with all reads issued up front
# speedup vs baseline: 1.0493x; 1.0086x over previous
; #define LAS __attribute__((address_space(3)))
; __device__ __forceinline__ unsigned pkbf(float lo, float hi) { typedef __bf16 b2 __attribute__((ext_vector_type(2))); f32x2 v = {lo, hi}; b2 b = __builtin_convertvector(v, b2); return __builtin_bit_cast(unsigned, b); }
; __device__ __forceinline__ int crow(int i, int h) { return (i & 3) + 8 * (i >> 2) + 4 * h; }
; #define MFMA32(a, b, c) __builtin_amdgcn_mfma_f32_32x32x16_bf16((a), (b), (c), 0, 0, 0)
; __device__ __forceinline__ void hgrn_phase(LAS unsigned char* lds, const bf16_t* mix, bf16_t* OFB, int item) {
;     ...
;         if (wid < 4) {
;             if (xb <= tb) {
;                 f32x16 a;
; #pragma unroll
;                 for (int i = 0; i < 16; ++i) a[i] = 0.f;
; #pragma unroll
;                 for (int kh = 0; kh < 2; ++kh) { bf16x8 A[4], B[4];
; #pragma unroll
;                     for (int ks = 0; ks < 4; ++ks) { A[ks] = *(LAS const bf16x8*)(lds + HG_QI + (32 * tb + r) * HG_P + (16 * (4 * kh + ks) + 8 * h) * 2);
;                         B[ks] = *(LAS const bf16x8*)(lds + HG_KI + (32 * xb + r) * HG_P + (16 * (4 * kh + ks) + 8 * h) * 2); }
; #pragma unroll
;                     for (int ks = 0; ks < 4; ++ks) a = MFMA32(A[ks], B[ks], a);
;                 }
; #pragma unroll
;                 for (int i = 0; i < 16; ++i) { const int t = 32 * tb + crow(i, h), s = 32 * xb + r; const float v = (s <= t) ? a[i] : 0.f;
;                     *(LAS bf16_t*)(lds + HG_AS + t * HG_ASP + s * 2) = (bf16_t)(pkbf(v, v) & 0xffffu); }
;             }
;         } else {
; #pragma unroll
;             for (int kh = 0; kh < 2; ++kh) { bf16x8 A[4], B[4];
; #pragma unroll
;                 for (int ks = 0; ks < 4; ++ks) { A[ks] = *(LAS const bf16x8*)(lds + HG_QG + (32 * tb + r) * HG_P + (16 * (4 * kh + ks) + 8 * h) * 2);
;                     B[ks] = *(LAS const bf16x8*)(lds + HG_ST + (32 * xb + r) * HG_P + (16 * (4 * kh + ks) + 8 * h) * 2); }
; #pragma unroll
;                 for (int ks = 0; ks < 4; ++ks) oacc = MFMA32(B[ks], A[ks], oacc);
;             }
;         }
.LBB0_513:
	s_waitcnt lgkmcnt(0)
	s_barrier
	v_cndmask_b32_e64 v1, 0, 1, s[6:7]
	v_cmp_ne_u32_e64 s[56:57], 1, v1
	s_andn2_b64 vcc, exec, s[6:7]
	s_mov_b64 s[92:93], -1
	s_cbranch_vccnz .LBB0_515
	v_add_u32_e32 v1, v73, v54
	v_add_u32_e32 v10, v72, v54
	s_mov_b64 s[92:93], 0
	ds_read_b128 v[2:5], v1
	ds_read_b128 v[6:9], v10 offset:34816
	ds_read_b128 v[204:207], v1 offset:32
	ds_read_b128 v[208:211], v10 offset:34848
	ds_read_b128 v[212:215], v1 offset:64
	ds_read_b128 v[216:219], v10 offset:34880
	ds_read_b128 v[220:223], v1 offset:96
	ds_read_b128 v[224:227], v10 offset:34912
	s_waitcnt lgkmcnt(6)
	v_mfma_f32_32x32x16_bf16 v[32:47], v[2:5], v[6:9], 0
	ds_read_b128 v[2:5], v1 offset:128
	ds_read_b128 v[6:9], v10 offset:34944
	s_waitcnt lgkmcnt(6)
	v_mfma_f32_32x32x16_bf16 v[32:47], v[204:207], v[208:211], v[32:47]
	ds_read_b128 v[204:207], v1 offset:160
	ds_read_b128 v[208:211], v10 offset:34976
	s_waitcnt lgkmcnt(6)
	v_mfma_f32_32x32x16_bf16 v[32:47], v[212:215], v[216:219], v[32:47]
	ds_read_b128 v[212:215], v1 offset:192
	ds_read_b128 v[216:219], v10 offset:35008
	s_waitcnt lgkmcnt(6)
	v_mfma_f32_32x32x16_bf16 v[32:47], v[220:223], v[224:227], v[32:47]
	ds_read_b128 v[220:223], v1 offset:224
	ds_read_b128 v[224:227], v10 offset:35040
	s_waitcnt lgkmcnt(6)
	v_mfma_f32_32x32x16_bf16 v[32:47], v[2:5], v[6:9], v[32:47]
	s_waitcnt lgkmcnt(4)
	v_mfma_f32_32x32x16_bf16 v[32:47], v[204:207], v[208:211], v[32:47]
	s_waitcnt lgkmcnt(2)
	v_mfma_f32_32x32x16_bf16 v[32:47], v[212:215], v[216:219], v[32:47]
	s_waitcnt lgkmcnt(0)
	v_mfma_f32_32x32x16_bf16 v[32:47], v[220:223], v[224:227], v[32:47]
.LBB0_515:
	s_andn2_b64 vcc, exec, s[92:93]
	s_cbranch_vccnz .LBB0_519
	s_andn2_b64 vcc, exec, s[0:1]
	s_cbranch_vccnz .LBB0_518
	v_add_u32_e32 v1, v72, v54
	ds_read_b128 v[2:5], v1
	ds_read_b128 v[6:9], v82 offset:17408
	ds_read_b128 v[204:207], v1 offset:32
	ds_read_b128 v[208:211], v82 offset:17440
	ds_read_b128 v[212:215], v1 offset:64
	ds_read_b128 v[216:219], v82 offset:17472
	ds_read_b128 v[220:223], v1 offset:96
	ds_read_b128 v[224:227], v82 offset:17504
	s_waitcnt lgkmcnt(6)
	v_mfma_f32_32x32x16_bf16 v[32:47], v[2:5], v[6:9], 0
	ds_read_b128 v[2:5], v1 offset:128
	ds_read_b128 v[6:9], v82 offset:17536
	s_waitcnt lgkmcnt(6)
	v_mfma_f32_32x32x16_bf16 v[32:47], v[204:207], v[208:211], v[32:47]
	ds_read_b128 v[204:207], v1 offset:160
	ds_read_b128 v[208:211], v82 offset:17568
	s_waitcnt lgkmcnt(6)
	v_mfma_f32_32x32x16_bf16 v[32:47], v[212:215], v[216:219], v[32:47]
	ds_read_b128 v[212:215], v1 offset:192
	ds_read_b128 v[216:219], v82 offset:17600
	s_waitcnt lgkmcnt(6)
	v_mfma_f32_32x32x16_bf16 v[32:47], v[220:223], v[224:227], v[32:47]
	ds_read_b128 v[220:223], v1 offset:224
	ds_read_b128 v[224:227], v82 offset:17632
	s_waitcnt lgkmcnt(6)
	v_mfma_f32_32x32x16_bf16 v[32:47], v[2:5], v[6:9], v[32:47]
	s_waitcnt lgkmcnt(4)
	v_mfma_f32_32x32x16_bf16 v[32:47], v[204:207], v[208:211], v[32:47]
	s_waitcnt lgkmcnt(2)
	v_mfma_f32_32x32x16_bf16 v[32:47], v[212:215], v[216:219], v[32:47]
	s_waitcnt lgkmcnt(0)
	v_mfma_f32_32x32x16_bf16 v[32:47], v[220:223], v[224:227], v[32:47]
	s_nop 11
	v_cvt_pk_bf16_f32 v1, v32, s0
	v_cvt_pk_bf16_f32 v2, v33, s0
	v_cvt_pk_bf16_f32 v3, v34, s0
	v_cvt_pk_bf16_f32 v4, v35, s0
	v_cvt_pk_bf16_f32 v5, v36, s0
	v_cvt_pk_bf16_f32 v6, v37, s0
	v_cvt_pk_bf16_f32 v7, v38, s0
	v_cvt_pk_bf16_f32 v8, v39, s0
	v_cvt_pk_bf16_f32 v9, v40, s0
	v_cvt_pk_bf16_f32 v10, v41, s0
	v_cvt_pk_bf16_f32 v11, v42, s0
	v_cvt_pk_bf16_f32 v12, v43, s0
	v_cvt_pk_bf16_f32 v13, v44, s0
	v_cvt_pk_bf16_f32 v14, v45, s0
	v_cvt_pk_bf16_f32 v15, v46, s0
	v_cvt_pk_bf16_f32 v32, v47, s0
	v_cndmask_b32_e64 v1, v1, 0, s[22:23]
	v_cndmask_b32_e64 v2, v2, 0, s[24:25]
	v_cndmask_b32_e64 v3, v3, 0, s[26:27]
	v_cndmask_b32_e64 v4, v4, 0, s[28:29]
	v_cndmask_b32_e64 v5, v5, 0, s[30:31]
	v_cndmask_b32_e64 v6, v6, 0, s[34:35]
	v_cndmask_b32_e64 v7, v7, 0, s[36:37]
	v_cndmask_b32_e64 v8, v8, 0, s[38:39]
	v_cndmask_b32_e64 v9, v9, 0, s[40:41]
	v_cndmask_b32_e64 v10, v10, 0, s[42:43]
	v_cndmask_b32_e64 v11, v11, 0, s[44:45]
	v_cndmask_b32_e64 v12, v12, 0, s[46:47]
	v_cndmask_b32_e64 v13, v13, 0, s[48:49]
	v_cndmask_b32_e64 v14, v14, 0, s[50:51]
	v_cndmask_b32_e64 v15, v15, 0, s[52:53]
	v_cndmask_b32_e64 v32, v32, 0, s[54:55]
	ds_write_b16 v83, v1
	ds_write_b16 v83, v2 offset:144
	ds_write_b16 v83, v3 offset:288
	ds_write_b16 v83, v4 offset:432
	ds_write_b16 v83, v5 offset:1152
	ds_write_b16 v83, v6 offset:1296
	ds_write_b16 v83, v7 offset:1440
	ds_write_b16 v83, v8 offset:1584
	ds_write_b16 v83, v9 offset:2304
	ds_write_b16 v83, v10 offset:2448
	ds_write_b16 v83, v11 offset:2592
	ds_write_b16 v83, v12 offset:2736
	ds_write_b16 v83, v13 offset:3456
	ds_write_b16 v83, v14 offset:3600
	ds_write_b16 v83, v15 offset:3744
	ds_write_b16 v83, v32 offset:3888

; #define LAS __attribute__((address_space(3)))
; __device__ __forceinline__ unsigned pkbf(float lo, float hi) { typedef __bf16 b2 __attribute__((ext_vector_type(2))); f32x2 v = {lo, hi}; b2 b = __builtin_convertvector(v, b2); return __builtin_bit_cast(unsigned, b); }
; #define MFMA32(a, b, c) __builtin_amdgcn_mfma_f32_32x32x16_bf16((a), (b), (c), 0, 0, 0)
; __device__ __forceinline__ s16x4 trrd(LAS const unsigned char* p) { return __builtin_bit_cast(s16x4, __builtin_amdgcn_ds_read_tr16_b64_v4i16((LAS v4i16_t*)p)); }
; __device__ __forceinline__ bf16x8 cat8(s16x4 lo, s16x4 hi) { return (bf16x8){lo[0], lo[1], lo[2], lo[3], hi[0], hi[1], hi[2], hi[3]}; }
; __device__ __forceinline__ void hgrn_phase(LAS unsigned char* lds, const bf16_t* mix, bf16_t* OFB, int item) {
;     ...
;         if (wid >= 4) {
;             const int nks = 2 * (tb + 1);
;             for (int ks = 0; ks < nks; ++ks) {
;                 const bf16x8 A = *(LAS const bf16x8*)(lds + HG_AS + (32 * tb + r) * HG_ASP + (16 * ks + 8 * h) * 2);
;                 LAS const unsigned char* vp = lds + HG_V + (16 * ks + trr) * HG_VP + (32 * xb + trc) * 2;
;                 const s16x4 lo = trrd(vp), hi = trrd(vp + 4 * HG_VP);
;                 oacc = MFMA32(cat8(lo, hi), A, oacc);
;             }
;             {
;               u32x2 p[4];
; #pragma unroll
;               for (int gq = 0; gq < 4; ++gq) { p[gq].x = pkbf(oacc[4 * gq], oacc[4 * gq + 1]); p[gq].y = pkbf(oacc[4 * gq + 2], oacc[4 * gq + 3]); }
;               bf16_t* orow = O + (tok0 + HG_TOK(c, 32 * tb + r)) * 512 + hh * 128 + dvh * 64 + 32 * xb + 8 * h;
; #pragma unroll
;               for (int gq = 0; gq < 4; gq += 2) {
;                   auto sx = __builtin_amdgcn_permlane32_swap(p[gq].x, p[gq + 1].x, false, false); auto sy = __builtin_amdgcn_permlane32_swap(p[gq].y, p[gq + 1].y, false, false);
;                   u32x4 w; w.x = sx[0]; w.y = sy[0]; w.z = sx[1]; w.w = sy[1];
;                   *(u32x4*)(orow + 8 * gq) = w; } }
;         }
.LBB0_520:
	v_add_u32_e32 v3, 0x11c00, v2
	ds_read_b128 v[4:7], v1
	ds_read_b64_tr_b16 v[8:9], v3
	ds_read_b64_tr_b16 v[10:11], v3 offset:768
	ds_read_b128 v[204:207], v1 offset:32
	ds_read_b64_tr_b16 v[208:209], v3 offset:3072
	ds_read_b64_tr_b16 v[210:211], v3 offset:3840
	s_cmp_eq_u32 s56, 2
	s_cbranch_scc1 .Lhg_two
	ds_read_b128 v[212:215], v1 offset:64
	ds_read_b64_tr_b16 v[216:217], v3 offset:6144
	ds_read_b64_tr_b16 v[218:219], v3 offset:6912
	ds_read_b128 v[220:223], v1 offset:96
	ds_read_b64_tr_b16 v[224:225], v3 offset:9216
	ds_read_b64_tr_b16 v[226:227], v3 offset:9984
	s_waitcnt lgkmcnt(9)
	v_mfma_f32_32x32x16_bf16 v[32:47], v[8:11], v[4:7], v[32:47]
	s_waitcnt lgkmcnt(6)
	v_mfma_f32_32x32x16_bf16 v[32:47], v[208:211], v[204:207], v[32:47]
	s_waitcnt lgkmcnt(3)
	v_mfma_f32_32x32x16_bf16 v[32:47], v[216:219], v[212:215], v[32:47]
	s_waitcnt lgkmcnt(0)
	v_mfma_f32_32x32x16_bf16 v[32:47], v[224:227], v[220:223], v[32:47]
	s_branch .Lhg_avdone
.Lhg_two:
	s_waitcnt lgkmcnt(3)
	v_mfma_f32_32x32x16_bf16 v[32:47], v[8:11], v[4:7], v[32:47]
	s_waitcnt lgkmcnt(0)
	v_mfma_f32_32x32x16_bf16 v[32:47], v[208:211], v[204:207], v[32:47]
.Lhg_avdone:
	s_lshl_b32 s56, s78, 6
	s_or_b32 s57, s86, s56
	v_subrev_u32_e32 v1, s57, v74
	v_or_b32_e32 v10, s56, v71
	v_cndmask_b32_e64 v10, v1, v10, s[4:5]
	v_ashrrev_i32_e32 v11, 31, v10
	v_lshl_add_u64 v[10:11], s[90:91], 0, v[10:11]
	s_nop 1
	v_cvt_pk_bf16_f32 v2, v32, v33
	v_cvt_pk_bf16_f32 v3, v34, v35
	v_cvt_pk_bf16_f32 v4, v36, v37
	v_cvt_pk_bf16_f32 v5, v38, v39
	v_cvt_pk_bf16_f32 v6, v40, v41
	v_cvt_pk_bf16_f32 v7, v42, v43
	v_cvt_pk_bf16_f32 v8, v44, v45
	v_cvt_pk_bf16_f32 v9, v46, v47
	v_lshlrev_b64 v[10:11], 10, v[10:11]
	v_lshl_add_u64 v[10:11], v[56:57], 0, v[10:11]
	v_permlane32_swap_b32_e32 v2, v4
	v_permlane32_swap_b32_e32 v3, v5
	v_permlane32_swap_b32_e32 v6, v8
	v_permlane32_swap_b32_e32 v7, v9
	global_store_dwordx4 v[10:11], v[2:5], off
	global_store_dwordx4 v[10:11], v[6:9], off offset:32
	s_branch .LBB0_506
